# X + attention: tile staging (register->LDS) and next global loads moved from before the tile's first MFMAs to behind its eight stage-1 S MFMAs
# speedup vs baseline: 1.0038x; 1.0038x over previous
; #define LAS __attribute__((address_space(3)))
;     ...
;     auto load_tile = [&](KVRegs& r, int t) {
;         const bf16* ks = Kp + (size_t)(t * 64 + kr) * ldkv; r.ka = *(const u32x4*)(ks + 8 * kj); r.kb = *(const u32x4*)(ks + 64 + 8 * kj);
;         if (MODE == 0) { const bf16* vs = Vp + (size_t)(tid >> 2) * SEQ + t * 64 + 16 * (tid & 3); r.va = *(const u32x4*)vs; r.vb = *(const u32x4*)(vs + 8); }
;         else { const bf16* vs = Vp + (size_t)(t * 64 + vr) * ldkv; r.va = *(const u32x4*)(vs + 8 * vj); r.vb = *(const u32x4*)(vs + 64 + 8 * vj); } };
;     auto stage = [&](KVRegs& r, int buf) {
;         LAS bf16* Ks = (LAS bf16*)(lds + koff(buf)); LAS bf16* VT = (LAS bf16*)(lds + voff(buf));
;         if (MODE >= 1) norm16(r.ka, r.kb, kg, 1.0f);
;         *(LAS u32x4*)(Ks + kr * QP + 8 * kj) = r.ka; *(LAS u32x4*)(Ks + kr * QP + 64 + 8 * kj) = r.kb;
;         if (MODE == 0) { *(LAS u32x4*)(VT + (tid >> 2) * VPA + 16 * (tid & 3)) = r.va; *(LAS u32x4*)(VT + (tid >> 2) * VPA + 16 * (tid & 3) + 8) = r.vb; }
;     ...
;             int b1 = cur + 1; if (b1 >= 3) b1 -= 3;
;             if (t + 3 < ntiles) { stage(r1, cur); if (t + 5 < ntiles) load_tile(r1, t + 5); }
.LBB0_121:
	v_pk_add_f32 v[142:143], v[142:143], 0 op_sel_hi:[1,0]
	s_add_i32 s78, s78, 0x9800
	v_pk_add_f32 v[140:141], v[140:141], v[142:143]
	s_cmp_lt_i32 s63, 2
	v_pk_add_f32 v[138:139], v[138:139], v[140:141]
	s_cselect_b32 s63, s78, 0
	v_pk_add_f32 v[136:137], v[136:137], v[138:139]
	s_add_i32 s63, s63, 0
	v_pk_add_f32 v[134:135], v[134:135], v[136:137]
	v_add_u32_e32 v171, s63, v165
	v_pk_add_f32 v[132:133], v[132:133], v[134:135]
	v_add_u32_e32 v182, v171, v167
	v_pk_add_f32 v[130:131], v[130:131], v[132:133]
	v_pk_add_f32 v[128:129], v[128:129], v[130:131]
	v_pk_add_f32 v[150:151], v[150:151], v[128:129]
	ds_read_b128 v[172:175], v182 offset:192
	ds_read_b128 v[192:195], v182 offset:4736
	ds_read_b128 v[196:199], v182 offset:4800
	ds_read2_b32 v[182:183], v170 offset0:80 offset1:81
	ds_read2_b32 v[184:185], v170 offset0:82 offset1:83
	ds_read2_b32 v[188:189], v170 offset0:96 offset1:97
	ds_read2_b32 v[190:191], v170 offset0:98 offset1:99
	s_waitcnt lgkmcnt(7)
	v_mfma_f32_16x16x32_bf16 v[200:203], v[228:231], v[76:79], 0
	v_mfma_f32_16x16x32_bf16 v[204:207], v[232:235], v[76:79], 0
	v_mfma_f32_16x16x32_bf16 v[200:203], v[240:243], v[80:83], v[200:203]
	v_mfma_f32_16x16x32_bf16 v[204:207], v[244:247], v[80:83], v[204:207]
	v_mfma_f32_16x16x32_bf16 v[200:203], v[248:251], v[84:87], v[200:203]
	s_waitcnt lgkmcnt(5)
	v_mfma_f32_16x16x32_bf16 v[204:207], v[192:195], v[84:87], v[204:207]
	v_mfma_f32_16x16x32_bf16 v[200:203], v[172:175], v[88:91], v[200:203]
	s_waitcnt lgkmcnt(4)
	v_mfma_f32_16x16x32_bf16 v[204:207], v[196:199], v[88:91], v[204:207]
	s_add_i32 s68, s41, -2
	s_cmp_ge_u32 s68, s40
	s_cbranch_scc1 .Lstage_b_done
	v_add3_u32 v144, s79, v149, v152
	s_add_i32 s68, s41, -1
	s_cmp_ge_u32 s68, s40
	s_cbranch_scc1 .Lattn_b_short
	s_waitcnt vmcnt(7)
	ds_write_b128 v144, v[48:51]
	s_waitcnt vmcnt(6)
	ds_write_b128 v144, v[52:55] offset:128
	v_add3_u32 v144, s79, v157, v148
	s_waitcnt vmcnt(4)
	s_branch .Lattn_b_join

; #define LAS __attribute__((address_space(3)))
; #define MMA16(X, Y, ACC) ACC = __builtin_amdgcn_mfma_f32_16x16x32_bf16((X), (Y), (ACC), 0, 0, 0)
;     ...
;         __builtin_amdgcn_sched_barrier(0);
;         bf16x8 vf[8];
; #pragma unroll
;         for (int db = 0; db < 8; ++db) vf[db] = *(const LAS bf16x8*)(VT + (16 * db + fr) * VPA + 32 * kh + 8 * fq);
;         if (MODE == 0) { const LAS float* bp = BT + (2047 - 16 - (q0 + 32 * rp + fr - t * 64 - 32 * kh - 4 * fq));
; #pragma unroll
;             for (int kb = 0; kb < 2; ++kb)
; #pragma unroll
;                 for (int i = 0; i < 4; ++i) bias[1][kb][i] = bp[16 * kb + i]; }
; #pragma unroll
;         for (int ks = 0; ks < 4; ++ks)
; #pragma unroll
;             for (int kb = 0; kb < 2; ++kb) MMA16(kf[kb][ks], qf[1][ks], s[1][kb]);
;         smax(0);
; #pragma unroll
;         for (int g = 0; g < 8; ++g) { __builtin_amdgcn_sched_group_barrier(0x008, 1, 0); __builtin_amdgcn_sched_group_barrier(0x100, 1, 0); __builtin_amdgcn_sched_group_barrier(0x002, 4, 0); }
;         __builtin_amdgcn_sched_barrier(0);
; #pragma unroll
;         for (int db = 0; db < 8; ++db) MMA16(vf[db], pf[0], o[0][db]);
;         smax(1);
; #pragma unroll
;         for (int g = 0; g < 8; ++g) { __builtin_amdgcn_sched_group_barrier(0x008, 1, 1); __builtin_amdgcn_sched_group_barrier(0x002, 4, 1); }
;         __builtin_amdgcn_sched_barrier(0);
; #pragma unroll
;         for (int db = 0; db < 8; ++db) MMA16(vf[db], pf[1], o[1][db]);
;         __builtin_amdgcn_sched_barrier(0);
;     };
.Lstage_b_done:
	v_mfma_f32_16x16x32_bf16 v[208:211], v[228:231], v[92:95], 0
	ds_read2_b32 v[212:213], v170 offset0:64 offset1:65
	v_add3_u32 v171, v171, v168, v169
	s_waitcnt lgkmcnt(3)
	s_nop 1
	v_pk_add_f32 v[184:185], v[184:185], v[202:203]
	v_pk_add_f32 v[182:183], v[182:183], v[200:201]
	s_waitcnt lgkmcnt(1)
	v_pk_add_f32 v[190:191], v[190:191], v[206:207]
	v_mfma_f32_16x16x32_bf16 v[136:139], v[232:235], v[92:95], 0
	ds_read_b128 v[128:131], v171 offset:36352
	v_pk_add_f32 v[188:189], v[188:189], v[204:205]
	v_exp_f32_e32 v207, v182
	v_mfma_f32_16x16x32_bf16 v[200:203], v[240:243], v[96:99], v[208:211]
	ds_read_b128 v[132:135], v171 offset:18432
	v_exp_f32_e32 v183, v183
	v_exp_f32_e32 v185, v185
	v_mfma_f32_16x16x32_bf16 v[144:147], v[244:247], v[96:99], v[136:139]
	v_exp_f32_e32 v209, v184
	v_exp_f32_e32 v211, v188
	v_exp_f32_e32 v189, v189
	ds_read_b128 v[136:139], v171 offset:20992
	v_mfma_f32_16x16x32_bf16 v[200:203], v[248:251], v[100:103], v[200:203]
	ds_read_b128 v[140:143], v171 offset:23552
	v_exp_f32_e32 v191, v191
	v_mfma_f32_16x16x32_bf16 v[192:195], v[192:195], v[100:103], v[144:147]
	s_nop 2
	ds_read_b128 v[144:147], v171 offset:26112
	v_mfma_f32_16x16x32_bf16 v[192:195], v[196:199], v[104:107], v[192:195]
	v_mfma_f32_16x16x32_bf16 v[172:175], v[172:175], v[104:107], v[200:203]
	ds_read2_b32 v[196:197], v170 offset0:66 offset1:67
	s_waitcnt lgkmcnt(0)
	s_nop 5
	v_pk_add_f32 v[174:175], v[196:197], v[174:175]
	ds_read_b128 v[196:199], v171 offset:33792
	v_exp_f32_e32 v208, v174
	v_exp_f32_e32 v184, v175
	ds_read2_b32 v[174:175], v170 offset0:82 offset1:83
	s_waitcnt lgkmcnt(0)
	v_pk_add_f32 v[174:175], v[174:175], v[194:195]
	ds_read2_b32 v[204:205], v170 offset0:80 offset1:81
	s_waitcnt lgkmcnt(0)
	v_pk_add_f32 v[192:193], v[204:205], v[192:193]
	v_pk_add_f32 v[172:173], v[212:213], v[172:173]
	v_exp_f32_e32 v210, v192
	v_exp_f32_e32 v206, v172
	v_exp_f32_e32 v182, v173
	v_exp_f32_e32 v188, v193
	v_exp_f32_e32 v213, v190
	v_pk_add_f32 v[172:173], v[206:207], 0 op_sel_hi:[1,0]
	v_exp_f32_e32 v212, v174
	v_pk_add_f32 v[172:173], v[182:183], v[172:173]
	v_exp_f32_e32 v190, v175
	v_pk_add_f32 v[172:173], v[208:209], v[172:173]
	ds_read_b128 v[192:195], v171 offset:31232
	v_pk_add_f32 v[172:173], v[184:185], v[172:173]
	s_nop 0
	v_pk_add_f32 v[172:173], v[210:211], v[172:173]
	s_nop 0
	v_pk_add_f32 v[172:173], v[188:189], v[172:173]
	s_nop 0
	v_pk_add_f32 v[172:173], v[212:213], v[172:173]
	s_nop 0
	v_pk_add_f32 v[204:205], v[190:191], v[172:173]
	ds_read_b128 v[172:175], v171 offset:28672
	v_cvt_pk_bf16_f32 v200, v207, v183
	v_cvt_pk_bf16_f32 v201, v209, v185
	v_cvt_pk_bf16_f32 v202, v211, v189
	v_cvt_pk_bf16_f32 v203, v213, v191
	s_nop 0
	v_mfma_f32_16x16x32_bf16 v[124:127], v[132:135], v[200:203], v[124:127]
	v_add_f32_e64 v150, v150, v204
	v_add_f32_e64 v151, v151, v205
	v_cvt_pk_bf16_f32 v204, v206, v182
	v_cvt_pk_bf16_f32 v205, v208, v184
	v_mfma_f32_16x16x32_bf16 v[120:123], v[136:139], v[200:203], v[120:123]
	v_cvt_pk_bf16_f32 v206, v210, v188
	v_cvt_pk_bf16_f32 v207, v212, v190
	v_mfma_f32_16x16x32_bf16 v[116:119], v[140:143], v[200:203], v[116:119]
	v_mfma_f32_16x16x32_bf16 v[112:115], v[144:147], v[200:203], v[112:115]
	s_waitcnt lgkmcnt(0)
	s_mul_i32 s69, s58, 0x9800
	v_add3_u32 v239, s69, v165, v167
	ds_read_b128 v[228:231], v239
	ds_read_b128 v[232:235], v239 offset:4608
	ds_read_b128 v[240:243], v239 offset:64
	ds_read_b128 v[244:247], v239 offset:4672
	ds_read_b128 v[248:251], v239 offset:128
	v_mfma_f32_16x16x32_bf16 v[108:111], v[172:175], v[200:203], v[108:111]
	v_mfma_f32_16x16x32_bf16 v[72:75], v[192:195], v[200:203], v[72:75]
	v_mfma_f32_16x16x32_bf16 v[68:71], v[196:199], v[200:203], v[68:71]
	v_mfma_f32_16x16x32_bf16 v[64:67], v[128:131], v[200:203], v[64:67]
	v_mfma_f32_16x16x32_bf16 v[28:31], v[132:135], v[204:207], v[28:31]
	v_mfma_f32_16x16x32_bf16 v[24:27], v[136:139], v[204:207], v[24:27]
	v_mfma_f32_16x16x32_bf16 v[20:23], v[140:143], v[204:207], v[20:23]
	v_mfma_f32_16x16x32_bf16 v[16:19], v[144:147], v[204:207], v[16:19]
	v_mfma_f32_16x16x32_bf16 v[12:15], v[172:175], v[204:207], v[12:15]
	v_mfma_f32_16x16x32_bf16 v[8:11], v[192:195], v[204:207], v[8:11]
	v_mfma_f32_16x16x32_bf16 v[4:7], v[196:199], v[204:207], v[4:7]
	v_mfma_f32_16x16x32_bf16 v[0:3], v[128:131], v[204:207], v[0:3]
	s_mov_b64 s[68:69], 0x100
	v_lshl_add_u64 v[158:159], v[158:159], 0, s[68:69]
	s_mov_b64 s[68:69], 0x180000
	s_add_i32 s41, s41, 2
	v_lshl_add_u64 v[160:161], v[160:161], 0, s[68:69]
	v_add_u32_e32 v170, 0x200, v170
	s_cmp_ge_u32 s59, s40
	s_mov_b32 s63, s58
	s_barrier
	s_cbranch_scc1 .LBB0_128

; #define LAS __attribute__((address_space(3)))
;     ...
;     auto load_tile = [&](KVRegs& r, int t) {
;         const bf16* ks = Kp + (size_t)(t * 64 + kr) * ldkv; r.ka = *(const u32x4*)(ks + 8 * kj); r.kb = *(const u32x4*)(ks + 64 + 8 * kj);
;         if (MODE == 0) { const bf16* vs = Vp + (size_t)(tid >> 2) * SEQ + t * 64 + 16 * (tid & 3); r.va = *(const u32x4*)vs; r.vb = *(const u32x4*)(vs + 8); }
;         else { const bf16* vs = Vp + (size_t)(t * 64 + vr) * ldkv; r.va = *(const u32x4*)(vs + 8 * vj); r.vb = *(const u32x4*)(vs + 64 + 8 * vj); } };
;     auto stage = [&](KVRegs& r, int buf) {
;         LAS bf16* Ks = (LAS bf16*)(lds + koff(buf)); LAS bf16* VT = (LAS bf16*)(lds + voff(buf));
;         if (MODE >= 1) norm16(r.ka, r.kb, kg, 1.0f);
;         *(LAS u32x4*)(Ks + kr * QP + 8 * kj) = r.ka; *(LAS u32x4*)(Ks + kr * QP + 64 + 8 * kj) = r.kb;
;         if (MODE == 0) { *(LAS u32x4*)(VT + (tid >> 2) * VPA + 16 * (tid & 3)) = r.va; *(LAS u32x4*)(VT + (tid >> 2) * VPA + 16 * (tid & 3) + 8) = r.vb; }
;     ...
;         for (int t = 0; t < ntiles; t += 2) {
;             int b2 = cur + 2; if (b2 >= 3) b2 -= 3;
;             if (t + 2 < ntiles) { stage(r0, b2); if (t + 4 < ntiles) load_tile(r0, t + 4); }
;             compute(cur, t);
;             __syncthreads();
.LBB0_125:
	s_mul_i32 s78, s63, 0x9800
	s_add_i32 s79, s78, 0
	v_add_u32_e32 v171, s79, v165
	v_add_u32_e32 v182, v171, v167
	ds_read_b128 v[140:143], v182 offset:192
	ds_read_b128 v[192:195], v182 offset:4736
	ds_read_b128 v[196:199], v182 offset:4800
	ds_read2_b32 v[182:183], v170 offset0:16 offset1:17
	ds_read2_b32 v[184:185], v170 offset0:18 offset1:19
	ds_read2_b32 v[188:189], v170 offset0:32 offset1:33
	ds_read2_b32 v[190:191], v170 offset0:34 offset1:35
	s_waitcnt lgkmcnt(7)
	v_mfma_f32_16x16x32_bf16 v[200:203], v[228:231], v[76:79], 0
	v_mfma_f32_16x16x32_bf16 v[204:207], v[232:235], v[76:79], 0
	v_mfma_f32_16x16x32_bf16 v[200:203], v[240:243], v[80:83], v[200:203]
	v_mfma_f32_16x16x32_bf16 v[204:207], v[244:247], v[80:83], v[204:207]
	v_mfma_f32_16x16x32_bf16 v[200:203], v[248:251], v[84:87], v[200:203]
	s_waitcnt lgkmcnt(5)
	v_mfma_f32_16x16x32_bf16 v[204:207], v[192:195], v[84:87], v[204:207]
	v_mfma_f32_16x16x32_bf16 v[200:203], v[140:143], v[88:91], v[200:203]
	s_waitcnt lgkmcnt(4)
	v_mfma_f32_16x16x32_bf16 v[204:207], v[196:199], v[88:91], v[204:207]
	s_cmp_ge_u32 s59, s40
	s_cbranch_scc1 .Lstage_a_done
	s_mul_i32 s68, s58, 0x9800
	s_add_i32 s68, s68, 0
	v_add3_u32 v128, s68, v149, v152
	s_waitcnt vmcnt(7)
	ds_write_b128 v128, v[32:35]
	s_waitcnt vmcnt(6)
	ds_write_b128 v128, v[36:39] offset:128
	v_add3_u32 v128, s68, v157, v148
	s_add_i32 s68, s41, -1
	s_cmp_ge_u32 s68, s40
	s_waitcnt vmcnt(4)
	ds_write_b128 v128, v[44:47] offset:18432
	ds_write_b128 v128, v[40:43] offset:18448
	s_cbranch_scc1 .Lstage_a_done
	global_load_dwordx4 v[32:35], v[160:161], off
	global_load_dwordx4 v[36:39], v[160:161], off offset:128
	global_load_dwordx4 v[40:43], v[158:159], off offset:16
	global_load_dwordx4 v[44:47], v[158:159], off
.Lstage_a_done:
	v_mfma_f32_16x16x32_bf16 v[128:131], v[228:231], v[92:95], 0
	ds_read2_b32 v[212:213], v170 offset1:1
	v_add3_u32 v171, v171, v168, v169
	s_waitcnt lgkmcnt(3)
	s_nop 1
	v_pk_add_f32 v[184:185], v[184:185], v[202:203]
	v_pk_add_f32 v[182:183], v[182:183], v[200:201]
	s_waitcnt lgkmcnt(1)
	v_pk_add_f32 v[190:191], v[190:191], v[206:207]
	v_mfma_f32_16x16x32_bf16 v[144:147], v[232:235], v[92:95], 0
	ds_read_b128 v[200:203], v171 offset:36352
	v_pk_add_f32 v[188:189], v[188:189], v[204:205]
	ds_read2_b32 v[224:225], v170 offset0:16 offset1:17
	v_mfma_f32_16x16x32_bf16 v[128:131], v[240:243], v[96:99], v[128:131]
	ds_read_b128 v[204:207], v171 offset:18432
	ds_read2_b32 v[226:227], v170 offset0:18 offset1:19
	ds_read_b128 v[216:219], v171 offset:33792
	v_mfma_f32_16x16x32_bf16 v[132:135], v[244:247], v[96:99], v[144:147]
	s_nop 2
	ds_read_b128 v[144:147], v171 offset:20992
	v_mfma_f32_16x16x32_bf16 v[128:131], v[248:251], v[100:103], v[128:131]
	ds_read_b128 v[172:175], v171 offset:23552
	v_exp_f32_e32 v139, v184
	v_exp_f32_e32 v137, v185
	v_mfma_f32_16x16x32_bf16 v[132:135], v[192:195], v[100:103], v[132:135]
	ds_read_b128 v[192:195], v171 offset:26112
	v_mfma_f32_16x16x32_bf16 v[128:131], v[140:143], v[104:107], v[128:131]
	ds_read_b128 v[208:211], v171 offset:28672
	v_exp_f32_e32 v143, v182
	v_exp_f32_e32 v141, v183
	s_waitcnt lgkmcnt(9)
	s_nop 3
	v_pk_add_f32 v[220:221], v[212:213], v[128:129]
	v_mfma_f32_16x16x32_bf16 v[196:199], v[196:199], v[104:107], v[132:135]
	ds_read2_b32 v[128:129], v170 offset0:2 offset1:3
	ds_read_b128 v[212:215], v171 offset:31232
	v_exp_f32_e32 v142, v220
	v_exp_f32_e32 v135, v188
	v_exp_f32_e32 v133, v189
	s_waitcnt lgkmcnt(1)
	v_pk_add_f32 v[222:223], v[128:129], v[130:131]
	s_nop 0
	v_pk_add_f32 v[182:183], v[226:227], v[198:199]
	v_pk_add_f32 v[184:185], v[224:225], v[196:197]
	v_exp_f32_e32 v131, v190
	v_exp_f32_e32 v129, v191
	v_exp_f32_e32 v140, v221
	v_exp_f32_e32 v138, v222
	v_exp_f32_e32 v136, v223
	v_exp_f32_e32 v134, v184
	v_exp_f32_e32 v132, v185
	v_exp_f32_e32 v130, v182
	v_exp_f32_e32 v128, v183
	v_cvt_pk_bf16_f32 v196, v143, v141
	v_cvt_pk_bf16_f32 v197, v139, v137
	v_cvt_pk_bf16_f32 v198, v135, v133
	v_cvt_pk_bf16_f32 v199, v131, v129
	s_nop 0
	v_mfma_f32_16x16x32_bf16 v[124:127], v[204:207], v[196:199], v[124:127]
	v_mfma_f32_16x16x32_bf16 v[120:123], v[144:147], v[196:199], v[120:123]
	v_mfma_f32_16x16x32_bf16 v[116:119], v[172:175], v[196:199], v[116:119]
	v_mfma_f32_16x16x32_bf16 v[112:115], v[192:195], v[196:199], v[112:115]
	v_mfma_f32_16x16x32_bf16 v[108:111], v[208:211], v[196:199], v[108:111]
	s_waitcnt lgkmcnt(0)
	s_add_i32 s69, s78, 0x9800
	s_cmp_lt_i32 s63, 2
	s_cselect_b32 s69, s69, 0
	v_add3_u32 v239, s69, v165, v167
	ds_read_b128 v[228:231], v239
	ds_read_b128 v[232:235], v239 offset:4608
	ds_read_b128 v[240:243], v239 offset:64
	ds_read_b128 v[244:247], v239 offset:4672
	ds_read_b128 v[248:251], v239 offset:128
	v_mfma_f32_16x16x32_bf16 v[72:75], v[212:215], v[196:199], v[72:75]
	v_mfma_f32_16x16x32_bf16 v[68:71], v[216:219], v[196:199], v[68:71]
	v_mfma_f32_16x16x32_bf16 v[64:67], v[200:203], v[196:199], v[64:67]
	v_cvt_pk_bf16_f32 v196, v142, v140
	v_cvt_pk_bf16_f32 v197, v138, v136
	v_cvt_pk_bf16_f32 v198, v134, v132
	v_cvt_pk_bf16_f32 v199, v130, v128
	s_nop 0
	v_mfma_f32_16x16x32_bf16 v[28:31], v[204:207], v[196:199], v[28:31]
	v_mfma_f32_16x16x32_bf16 v[24:27], v[144:147], v[196:199], v[24:27]
	v_mfma_f32_16x16x32_bf16 v[20:23], v[172:175], v[196:199], v[20:23]
	v_mfma_f32_16x16x32_bf16 v[16:19], v[192:195], v[196:199], v[16:19]
	v_mfma_f32_16x16x32_bf16 v[12:15], v[208:211], v[196:199], v[12:15]
	v_mfma_f32_16x16x32_bf16 v[8:11], v[212:215], v[196:199], v[8:11]
	v_mfma_f32_16x16x32_bf16 v[4:7], v[216:219], v[196:199], v[4:7]
	v_mfma_f32_16x16x32_bf16 v[0:3], v[200:203], v[196:199], v[0:3]
	s_barrier
	s_branch .LBB0_121
